# v017 + FFN-down epilogue row-sum reduction with v_permlane16/32_swap instead of ds_bpermute (no LDS round trips)
# speedup vs baseline: 1.0010x; 1.0010x over previous
.LBB0_356:
	v_lshl_add_u32 v144, s11, 8, v1
	v_ashrrev_i32_e32 v145, 31, v144
	v_lshl_or_b32 v142, s10, 8, v147
	v_lshlrev_b64 v[140:141], 12, v[144:145]
	v_ashrrev_i32_e32 v143, 31, v142
	v_lshl_add_u64 v[140:141], s[94:95], 0, v[140:141]
	v_lshl_add_u64 v[140:141], v[142:143], 1, v[140:141]
	global_load_dwordx4 v[150:153], v[140:141], off
	s_waitcnt vmcnt(0)
	v_lshlrev_b32_e32 v149, 16, v150
	v_and_b32_e32 v150, 0xffff0000, v150
	v_lshlrev_b32_e32 v154, 16, v151
	v_and_b32_e32 v151, 0xffff0000, v151
	v_lshlrev_b32_e32 v155, 16, v152
	v_and_b32_e32 v152, 0xffff0000, v152
	v_lshlrev_b32_e32 v156, 16, v153
	v_and_b32_e32 v153, 0xffff0000, v153
	v_fmac_f32_e32 v150, 0.5, v127
	v_fmac_f32_e32 v151, 0.5, v129
	v_fmac_f32_e32 v152, 0.5, v123
	v_fmac_f32_e32 v153, 0.5, v125
	v_fmac_f32_e32 v149, 0.5, v126
	v_fmac_f32_e32 v154, 0.5, v128
	v_fmac_f32_e32 v155, 0.5, v122
	v_fmac_f32_e32 v156, 0.5, v124
	v_cvt_pk_bf16_f32 v124, v149, v150
	v_cvt_pk_bf16_f32 v125, v154, v151
	v_cvt_pk_bf16_f32 v126, v155, v152
	v_cvt_pk_bf16_f32 v127, v156, v153
	global_load_dwordx4 v[150:153], v[140:141], off offset:256
	v_lshlrev_b32_e32 v128, 16, v124
	global_store_dwordx4 v[140:141], v[124:127], off
	v_lshlrev_b32_e32 v129, 16, v125
	v_lshlrev_b32_e32 v149, 16, v126
	v_and_b32_e32 v124, 0xffff0000, v124
	v_and_b32_e32 v125, 0xffff0000, v125
	v_and_b32_e32 v126, 0xffff0000, v126
	v_lshlrev_b32_e32 v154, 16, v127
	v_and_b32_e32 v127, 0xffff0000, v127
	v_mul_f32_e32 v124, v124, v124
	v_mul_f32_e32 v125, v125, v125
	v_mul_f32_e32 v126, v126, v126
	v_mul_f32_e32 v127, v127, v127
	v_fmac_f32_e32 v124, v128, v128
	v_fmac_f32_e32 v125, v129, v129
	v_fmac_f32_e32 v126, v149, v149
	v_fmac_f32_e32 v127, v154, v154
	v_add_f32_e32 v124, v124, v125
	v_add_f32_e32 v125, v126, v127
	v_add_f32_e32 v128, v124, v125
	v_and_b32_e32 v123, 64, v212
	v_xor_b32_e32 v122, 16, v212
	v_add_u32_e32 v123, 64, v123
	v_cmp_lt_i32_e32 vcc, v122, v123
	s_waitcnt vmcnt(1)
	v_lshlrev_b32_e32 v124, 16, v150
	v_and_b32_e32 v125, 0xffff0000, v150
	v_lshlrev_b32_e32 v126, 16, v151
	v_and_b32_e32 v127, 0xffff0000, v151
	v_lshlrev_b32_e32 v129, 16, v152
	v_and_b32_e32 v149, 0xffff0000, v152
	v_lshlrev_b32_e32 v150, 16, v153
	v_and_b32_e32 v151, 0xffff0000, v153
	v_fmac_f32_e32 v124, 0.5, v118
	v_fmac_f32_e32 v125, 0.5, v119
	v_fmac_f32_e32 v126, 0.5, v120
	v_fmac_f32_e32 v127, 0.5, v121
	v_fmac_f32_e32 v129, 0.5, v114
	v_fmac_f32_e32 v149, 0.5, v115
	v_fmac_f32_e32 v150, 0.5, v116
	v_fmac_f32_e32 v151, 0.5, v117
	v_cvt_pk_bf16_f32 v124, v124, v125
	v_cvt_pk_bf16_f32 v125, v126, v127
	v_cvt_pk_bf16_f32 v126, v129, v149
	v_cvt_pk_bf16_f32 v127, v150, v151
	v_cndmask_b32_e32 v122, v212, v122, vcc
	v_and_b32_e32 v115, 0xffff0000, v124
	v_and_b32_e32 v117, 0xffff0000, v125
	v_and_b32_e32 v119, 0xffff0000, v126
	v_and_b32_e32 v121, 0xffff0000, v127
	v_lshlrev_b32_e32 v114, 16, v124
	v_lshlrev_b32_e32 v116, 16, v125
	v_lshlrev_b32_e32 v118, 16, v126
	v_lshlrev_b32_e32 v120, 16, v127
	v_mul_f32_e32 v115, v115, v115
	v_mul_f32_e32 v117, v117, v117
	v_mul_f32_e32 v119, v119, v119
	v_mul_f32_e32 v121, v121, v121
	v_fmac_f32_e32 v115, v114, v114
	v_fmac_f32_e32 v117, v116, v116
	v_fmac_f32_e32 v119, v118, v118
	v_fmac_f32_e32 v121, v120, v120
	v_add_f32_e32 v114, v115, v117
	v_add_f32_e32 v115, v119, v121
	v_add_f32_e32 v114, v114, v115
	v_lshlrev_b32_e32 v122, 2, v122
	v_add_f32_e32 v114, v128, v114
	v_mov_b32_e32 v206, v114
	v_mov_b32_e32 v207, v114
	s_nop 1
	v_permlane16_swap_b32_e32 v206, v207
	v_xor_b32_e32 v116, 32, v212
	v_cmp_lt_i32_e32 vcc, v116, v123
	global_store_dwordx4 v[140:141], v[124:127], off offset:256
	s_waitcnt lgkmcnt(0)
	v_add_f32_e32 v117, v206, v207
	v_cndmask_b32_e32 v116, v212, v116, vcc
	v_lshlrev_b32_e32 v116, 2, v116
	v_mov_b32_e32 v206, v117
	v_mov_b32_e32 v207, v117
	s_nop 1
	v_permlane32_swap_b32_e32 v206, v207
	v_lshl_add_u64 v[114:115], v[144:145], 3, s[8:9]
	s_and_saveexec_b64 s[0:1], s[40:41]
	s_cbranch_execz .LBB0_358
	s_waitcnt lgkmcnt(0)
	v_add_f32_e32 v117, v206, v207
	v_fma_f32 v117, v117, s6, 0.5
	v_trunc_f32_e32 v117, v117
	v_mul_f32_e32 v118, 0x2f800000, v117
	v_floor_f32_e32 v119, v118
	v_fmac_f32_e32 v117, 0xcf800000, v119
	v_cvt_u32_f32_e32 v118, v117
	v_cvt_u32_f32_e32 v119, v119
	v_mov_b32_e32 v168, v118
	v_mov_b32_e32 v169, v119
.LBB0_358:
	s_or_b64 exec, exec, s[0:1]
	s_waitcnt lgkmcnt(0)
	v_or_b32_e32 v118, 16, v144
	v_ashrrev_i32_e32 v119, 31, v118
	v_lshlrev_b64 v[118:119], 12, v[118:119]
	v_lshl_add_u64 v[118:119], s[94:95], 0, v[118:119]
	v_lshl_add_u64 v[124:125], v[142:143], 1, v[118:119]
	global_load_dwordx4 v[118:121], v[124:125], off
	s_waitcnt vmcnt(0)
	v_lshlrev_b32_e32 v117, 16, v118
	v_and_b32_e32 v118, 0xffff0000, v118
	v_lshlrev_b32_e32 v123, 16, v119
	v_and_b32_e32 v119, 0xffff0000, v119
	v_lshlrev_b32_e32 v126, 16, v120
	v_and_b32_e32 v120, 0xffff0000, v120
	v_lshlrev_b32_e32 v127, 16, v121
	v_and_b32_e32 v121, 0xffff0000, v121
	v_fmac_f32_e32 v117, 0.5, v110
	v_fmac_f32_e32 v118, 0.5, v111
	v_fmac_f32_e32 v123, 0.5, v112
	v_fmac_f32_e32 v119, 0.5, v113
	v_fmac_f32_e32 v126, 0.5, v106
	v_fmac_f32_e32 v120, 0.5, v107
	v_fmac_f32_e32 v127, 0.5, v108
	v_fmac_f32_e32 v121, 0.5, v109
	v_cvt_pk_bf16_f32 v106, v117, v118
	v_cvt_pk_bf16_f32 v107, v123, v119
	v_cvt_pk_bf16_f32 v108, v126, v120
	v_cvt_pk_bf16_f32 v109, v127, v121
	global_load_dwordx4 v[110:113], v[124:125], off offset:256
	v_lshlrev_b32_e32 v117, 16, v106
	global_store_dwordx4 v[124:125], v[106:109], off
	v_lshlrev_b32_e32 v118, 16, v107
	v_lshlrev_b32_e32 v119, 16, v108
	v_and_b32_e32 v106, 0xffff0000, v106
	v_and_b32_e32 v107, 0xffff0000, v107
	v_and_b32_e32 v108, 0xffff0000, v108
	v_lshlrev_b32_e32 v120, 16, v109
	v_and_b32_e32 v109, 0xffff0000, v109
	v_mul_f32_e32 v106, v106, v106
	v_mul_f32_e32 v107, v107, v107
	v_mul_f32_e32 v108, v108, v108
	v_mul_f32_e32 v109, v109, v109
	v_fmac_f32_e32 v106, v117, v117
	v_fmac_f32_e32 v107, v118, v118
	v_fmac_f32_e32 v108, v119, v119
	v_fmac_f32_e32 v109, v120, v120
	v_add_f32_e32 v106, v106, v107
	v_add_f32_e32 v107, v108, v109
	v_add_f32_e32 v106, v106, v107
	s_waitcnt vmcnt(1)
	v_lshlrev_b32_e32 v107, 16, v110
	v_and_b32_e32 v108, 0xffff0000, v110
	v_and_b32_e32 v110, 0xffff0000, v111
	v_lshlrev_b32_e32 v109, 16, v111
	v_lshlrev_b32_e32 v111, 16, v112
	v_and_b32_e32 v112, 0xffff0000, v112
	v_lshlrev_b32_e32 v117, 16, v113
	v_and_b32_e32 v113, 0xffff0000, v113
	v_fmac_f32_e32 v108, 0.5, v103
	v_fmac_f32_e32 v110, 0.5, v105
	v_fmac_f32_e32 v107, 0.5, v102
	v_fmac_f32_e32 v109, 0.5, v104
	v_fmac_f32_e32 v111, 0.5, v98
	v_fmac_f32_e32 v112, 0.5, v99
	v_fmac_f32_e32 v117, 0.5, v100
	v_fmac_f32_e32 v113, 0.5, v101
	v_cvt_pk_bf16_f32 v100, v107, v108
	v_cvt_pk_bf16_f32 v101, v109, v110
	v_cvt_pk_bf16_f32 v102, v111, v112
	v_cvt_pk_bf16_f32 v103, v117, v113
	global_store_dwordx4 v[124:125], v[100:103], off offset:256
	v_and_b32_e32 v99, 0xffff0000, v100
	v_and_b32_e32 v105, 0xffff0000, v101
	v_and_b32_e32 v108, 0xffff0000, v102
	v_and_b32_e32 v110, 0xffff0000, v103
	v_lshlrev_b32_e32 v98, 16, v100
	v_lshlrev_b32_e32 v104, 16, v101
	v_lshlrev_b32_e32 v107, 16, v102
	v_lshlrev_b32_e32 v109, 16, v103
	v_mul_f32_e32 v99, v99, v99
	v_mul_f32_e32 v105, v105, v105
	v_mul_f32_e32 v108, v108, v108
	v_mul_f32_e32 v110, v110, v110
	v_fmac_f32_e32 v99, v98, v98
	v_fmac_f32_e32 v105, v104, v104
	v_fmac_f32_e32 v108, v107, v107
	v_fmac_f32_e32 v110, v109, v109
	v_add_f32_e32 v98, v99, v105
	v_add_f32_e32 v99, v108, v110
	v_add_f32_e32 v98, v98, v99
	v_add_f32_e32 v98, v106, v98
	v_mov_b32_e32 v206, v98
	v_mov_b32_e32 v207, v98
	s_nop 1
	v_permlane16_swap_b32_e32 v206, v207
	s_waitcnt lgkmcnt(0)
	v_add_f32_e32 v98, v206, v207
	v_mov_b32_e32 v206, v98
	v_mov_b32_e32 v207, v98
	s_nop 1
	v_permlane32_swap_b32_e32 v206, v207
	s_and_saveexec_b64 s[0:1], s[40:41]
	s_cbranch_execz .LBB0_360
	s_waitcnt lgkmcnt(0)
	v_add_f32_e32 v98, v206, v207
	v_fma_f32 v98, v98, s6, 0.5
	v_trunc_f32_e32 v98, v98
	v_mul_f32_e32 v99, 0x2f800000, v98
	v_floor_f32_e32 v99, v99
	v_fmac_f32_e32 v98, 0xcf800000, v99
	v_cvt_u32_f32_e32 v98, v98
	v_cvt_u32_f32_e32 v99, v99
	v_mov_b32_e32 v170, v98
	v_mov_b32_e32 v171, v99
.LBB0_360:
	s_or_b64 exec, exec, s[0:1]
	v_or_b32_e32 v98, 32, v144
	s_waitcnt lgkmcnt(0)
	v_ashrrev_i32_e32 v99, 31, v98
	v_lshlrev_b64 v[98:99], 12, v[98:99]
	v_lshl_add_u64 v[98:99], s[94:95], 0, v[98:99]
	v_lshl_add_u64 v[102:103], v[142:143], 1, v[98:99]
	global_load_dwordx4 v[98:101], v[102:103], off
	s_waitcnt vmcnt(0)
	v_lshlrev_b32_e32 v104, 16, v98
	v_and_b32_e32 v98, 0xffff0000, v98
	v_lshlrev_b32_e32 v105, 16, v99
	v_and_b32_e32 v99, 0xffff0000, v99
	v_lshlrev_b32_e32 v106, 16, v100
	v_and_b32_e32 v100, 0xffff0000, v100
	v_lshlrev_b32_e32 v107, 16, v101
	v_and_b32_e32 v101, 0xffff0000, v101
	v_fmac_f32_e32 v104, 0.5, v94
	v_fmac_f32_e32 v98, 0.5, v95
	v_fmac_f32_e32 v105, 0.5, v96
	v_fmac_f32_e32 v99, 0.5, v97
	v_fmac_f32_e32 v106, 0.5, v90
	v_fmac_f32_e32 v100, 0.5, v91
	v_fmac_f32_e32 v107, 0.5, v92
	v_fmac_f32_e32 v101, 0.5, v93
	v_cvt_pk_bf16_f32 v90, v104, v98
	v_cvt_pk_bf16_f32 v91, v105, v99
	v_cvt_pk_bf16_f32 v92, v106, v100
	v_cvt_pk_bf16_f32 v93, v107, v101
	global_load_dwordx4 v[94:97], v[102:103], off offset:256
	v_lshlrev_b32_e32 v98, 16, v90
	global_store_dwordx4 v[102:103], v[90:93], off
	v_lshlrev_b32_e32 v99, 16, v91
	v_lshlrev_b32_e32 v100, 16, v92
	v_and_b32_e32 v90, 0xffff0000, v90
	v_and_b32_e32 v91, 0xffff0000, v91
	v_and_b32_e32 v92, 0xffff0000, v92
	v_lshlrev_b32_e32 v101, 16, v93
	v_and_b32_e32 v93, 0xffff0000, v93
	v_mul_f32_e32 v90, v90, v90
	v_mul_f32_e32 v91, v91, v91
	v_mul_f32_e32 v92, v92, v92
	v_mul_f32_e32 v93, v93, v93
	v_fmac_f32_e32 v90, v98, v98
	v_fmac_f32_e32 v91, v99, v99
	v_fmac_f32_e32 v92, v100, v100
	v_fmac_f32_e32 v93, v101, v101
	v_add_f32_e32 v90, v90, v91
	v_add_f32_e32 v91, v92, v93
	v_add_f32_e32 v90, v90, v91
	s_waitcnt vmcnt(1)
	v_lshlrev_b32_e32 v91, 16, v94
	v_and_b32_e32 v92, 0xffff0000, v94
	v_and_b32_e32 v94, 0xffff0000, v95
	v_lshlrev_b32_e32 v93, 16, v95
	v_lshlrev_b32_e32 v95, 16, v96
	v_and_b32_e32 v96, 0xffff0000, v96
	v_lshlrev_b32_e32 v98, 16, v97
	v_and_b32_e32 v97, 0xffff0000, v97
	v_fmac_f32_e32 v92, 0.5, v87
	v_fmac_f32_e32 v94, 0.5, v89
	v_fmac_f32_e32 v91, 0.5, v86
	v_fmac_f32_e32 v93, 0.5, v88
	v_fmac_f32_e32 v95, 0.5, v82
	v_fmac_f32_e32 v96, 0.5, v83
	v_fmac_f32_e32 v98, 0.5, v84
	v_fmac_f32_e32 v97, 0.5, v85
	v_cvt_pk_bf16_f32 v84, v91, v92
	v_cvt_pk_bf16_f32 v85, v93, v94
	v_cvt_pk_bf16_f32 v86, v95, v96
	v_cvt_pk_bf16_f32 v87, v98, v97
	global_store_dwordx4 v[102:103], v[84:87], off offset:256
	v_and_b32_e32 v83, 0xffff0000, v84
	v_and_b32_e32 v89, 0xffff0000, v85
	v_and_b32_e32 v92, 0xffff0000, v86
	v_and_b32_e32 v94, 0xffff0000, v87
	v_lshlrev_b32_e32 v82, 16, v84
	v_lshlrev_b32_e32 v88, 16, v85
	v_lshlrev_b32_e32 v91, 16, v86
	v_lshlrev_b32_e32 v93, 16, v87
	v_mul_f32_e32 v83, v83, v83
	v_mul_f32_e32 v89, v89, v89
	v_mul_f32_e32 v92, v92, v92
	v_mul_f32_e32 v94, v94, v94
	v_fmac_f32_e32 v83, v82, v82
	v_fmac_f32_e32 v89, v88, v88
	v_fmac_f32_e32 v92, v91, v91
	v_fmac_f32_e32 v94, v93, v93
	v_add_f32_e32 v82, v83, v89
	v_add_f32_e32 v83, v92, v94
	v_add_f32_e32 v82, v82, v83
	v_add_f32_e32 v82, v90, v82
	v_mov_b32_e32 v206, v82
	v_mov_b32_e32 v207, v82
	s_nop 1
	v_permlane16_swap_b32_e32 v206, v207
	s_waitcnt lgkmcnt(0)
	v_add_f32_e32 v82, v206, v207
	v_mov_b32_e32 v206, v82
	v_mov_b32_e32 v207, v82
	s_nop 1
	v_permlane32_swap_b32_e32 v206, v207
	s_and_saveexec_b64 s[0:1], s[40:41]
	s_cbranch_execz .LBB0_362
	s_waitcnt lgkmcnt(0)
	v_add_f32_e32 v82, v206, v207
	v_fma_f32 v82, v82, s6, 0.5
	v_trunc_f32_e32 v82, v82
	v_mul_f32_e32 v83, 0x2f800000, v82
	v_floor_f32_e32 v83, v83
	v_fmac_f32_e32 v82, 0xcf800000, v83
	v_cvt_u32_f32_e32 v82, v82
	v_cvt_u32_f32_e32 v83, v83
	v_mov_b32_e32 v172, v82
	v_mov_b32_e32 v173, v83
.LBB0_362:
	s_or_b64 exec, exec, s[0:1]
	v_or_b32_e32 v82, 48, v144
	s_waitcnt lgkmcnt(0)
	v_ashrrev_i32_e32 v83, 31, v82
	v_lshlrev_b64 v[82:83], 12, v[82:83]
	v_lshl_add_u64 v[82:83], s[94:95], 0, v[82:83]
	v_lshl_add_u64 v[86:87], v[142:143], 1, v[82:83]
	global_load_dwordx4 v[82:85], v[86:87], off
	s_waitcnt vmcnt(0)
	v_lshlrev_b32_e32 v88, 16, v82
	v_and_b32_e32 v82, 0xffff0000, v82
	v_lshlrev_b32_e32 v89, 16, v83
	v_and_b32_e32 v83, 0xffff0000, v83
	v_lshlrev_b32_e32 v90, 16, v84
	v_and_b32_e32 v84, 0xffff0000, v84
	v_lshlrev_b32_e32 v91, 16, v85
	v_and_b32_e32 v85, 0xffff0000, v85
	v_fmac_f32_e32 v88, 0.5, v78
	v_fmac_f32_e32 v82, 0.5, v79
	v_fmac_f32_e32 v89, 0.5, v80
	v_fmac_f32_e32 v83, 0.5, v81
	v_fmac_f32_e32 v90, 0.5, v74
	v_fmac_f32_e32 v84, 0.5, v75
	v_fmac_f32_e32 v91, 0.5, v76
	v_fmac_f32_e32 v85, 0.5, v77
	v_cvt_pk_bf16_f32 v74, v88, v82
	v_cvt_pk_bf16_f32 v75, v89, v83
	v_cvt_pk_bf16_f32 v76, v90, v84
	v_cvt_pk_bf16_f32 v77, v91, v85
	global_load_dwordx4 v[78:81], v[86:87], off offset:256
	v_lshlrev_b32_e32 v82, 16, v74
	global_store_dwordx4 v[86:87], v[74:77], off
	v_lshlrev_b32_e32 v83, 16, v75
	v_lshlrev_b32_e32 v84, 16, v76
	v_and_b32_e32 v74, 0xffff0000, v74
	v_and_b32_e32 v75, 0xffff0000, v75
	v_and_b32_e32 v76, 0xffff0000, v76
	v_lshlrev_b32_e32 v85, 16, v77
	v_and_b32_e32 v77, 0xffff0000, v77
	v_mul_f32_e32 v74, v74, v74
	v_mul_f32_e32 v75, v75, v75
	v_mul_f32_e32 v76, v76, v76
	v_mul_f32_e32 v77, v77, v77
	v_fmac_f32_e32 v74, v82, v82
	v_fmac_f32_e32 v75, v83, v83
	v_fmac_f32_e32 v76, v84, v84
	v_fmac_f32_e32 v77, v85, v85
	v_add_f32_e32 v74, v74, v75
	v_add_f32_e32 v75, v76, v77
	v_add_f32_e32 v74, v74, v75
	s_waitcnt vmcnt(1)
	v_lshlrev_b32_e32 v75, 16, v78
	v_and_b32_e32 v76, 0xffff0000, v78
	v_and_b32_e32 v78, 0xffff0000, v79
	v_lshlrev_b32_e32 v77, 16, v79
	v_lshlrev_b32_e32 v79, 16, v80
	v_and_b32_e32 v80, 0xffff0000, v80
	v_lshlrev_b32_e32 v82, 16, v81
	v_and_b32_e32 v81, 0xffff0000, v81
	v_fmac_f32_e32 v76, 0.5, v71
	v_fmac_f32_e32 v78, 0.5, v73
	v_fmac_f32_e32 v75, 0.5, v70
	v_fmac_f32_e32 v77, 0.5, v72
	v_fmac_f32_e32 v79, 0.5, v66
	v_fmac_f32_e32 v80, 0.5, v67
	v_fmac_f32_e32 v82, 0.5, v68
	v_fmac_f32_e32 v81, 0.5, v69
	v_cvt_pk_bf16_f32 v68, v75, v76
	v_cvt_pk_bf16_f32 v69, v77, v78
	v_cvt_pk_bf16_f32 v70, v79, v80
	v_cvt_pk_bf16_f32 v71, v82, v81
	global_store_dwordx4 v[86:87], v[68:71], off offset:256
	v_and_b32_e32 v67, 0xffff0000, v68
	v_and_b32_e32 v73, 0xffff0000, v69
	v_and_b32_e32 v76, 0xffff0000, v70
	v_and_b32_e32 v78, 0xffff0000, v71
	v_lshlrev_b32_e32 v66, 16, v68
	v_lshlrev_b32_e32 v72, 16, v69
	v_lshlrev_b32_e32 v75, 16, v70
	v_lshlrev_b32_e32 v77, 16, v71
	v_mul_f32_e32 v67, v67, v67
	v_mul_f32_e32 v73, v73, v73
	v_mul_f32_e32 v76, v76, v76
	v_mul_f32_e32 v78, v78, v78
	v_fmac_f32_e32 v67, v66, v66
	v_fmac_f32_e32 v73, v72, v72
	v_fmac_f32_e32 v76, v75, v75
	v_fmac_f32_e32 v78, v77, v77
	v_add_f32_e32 v66, v67, v73
	v_add_f32_e32 v67, v76, v78
	v_add_f32_e32 v66, v66, v67
	v_add_f32_e32 v66, v74, v66
	v_mov_b32_e32 v206, v66
	v_mov_b32_e32 v207, v66
	s_nop 1
	v_permlane16_swap_b32_e32 v206, v207
	s_waitcnt lgkmcnt(0)
	v_add_f32_e32 v66, v206, v207
	v_mov_b32_e32 v206, v66
	v_mov_b32_e32 v207, v66
	s_nop 1
	v_permlane32_swap_b32_e32 v206, v207
	s_and_saveexec_b64 s[0:1], s[40:41]
	s_cbranch_execz .LBB0_364
	s_waitcnt lgkmcnt(0)
	v_add_f32_e32 v66, v206, v207
	v_fma_f32 v66, v66, s6, 0.5
	v_trunc_f32_e32 v66, v66
	v_mul_f32_e32 v67, 0x2f800000, v66
	v_floor_f32_e32 v67, v67
	v_fmac_f32_e32 v66, 0xcf800000, v67
	v_cvt_u32_f32_e32 v66, v66
	v_cvt_u32_f32_e32 v67, v67
	v_mov_b32_e32 v174, v66
	v_mov_b32_e32 v175, v67
.LBB0_364:
	s_or_b64 exec, exec, s[0:1]
	v_add_co_u32_e32 v70, vcc, 0x80000, v140
	s_mov_b64 s[0:1], 0x80000
	s_nop 0
	v_addc_co_u32_e32 v71, vcc, 0, v141, vcc
	s_waitcnt lgkmcnt(0)
	global_load_dwordx4 v[66:69], v[70:71], off
	v_lshl_add_u64 v[72:73], v[140:141], 0, s[0:1]
	s_waitcnt vmcnt(0)
	v_lshlrev_b32_e32 v74, 16, v66
	v_and_b32_e32 v66, 0xffff0000, v66
	v_lshlrev_b32_e32 v75, 16, v67
	v_and_b32_e32 v67, 0xffff0000, v67
	v_lshlrev_b32_e32 v76, 16, v68
	v_and_b32_e32 v68, 0xffff0000, v68
	v_lshlrev_b32_e32 v77, 16, v69
	v_and_b32_e32 v69, 0xffff0000, v69
	v_fmac_f32_e32 v74, 0.5, v62
	v_fmac_f32_e32 v66, 0.5, v63
	v_fmac_f32_e32 v75, 0.5, v64
	v_fmac_f32_e32 v67, 0.5, v65
	v_fmac_f32_e32 v76, 0.5, v58
	v_fmac_f32_e32 v68, 0.5, v59
	v_fmac_f32_e32 v77, 0.5, v60
	v_fmac_f32_e32 v69, 0.5, v61
	v_cvt_pk_bf16_f32 v58, v74, v66
	v_cvt_pk_bf16_f32 v59, v75, v67
	v_cvt_pk_bf16_f32 v60, v76, v68
	v_cvt_pk_bf16_f32 v61, v77, v69
	global_load_dwordx4 v[62:65], v[72:73], off offset:256
	v_lshlrev_b32_e32 v66, 16, v58
	global_store_dwordx4 v[70:71], v[58:61], off
	v_lshlrev_b32_e32 v67, 16, v59
	v_lshlrev_b32_e32 v68, 16, v60
	v_and_b32_e32 v58, 0xffff0000, v58
	v_and_b32_e32 v59, 0xffff0000, v59
	v_and_b32_e32 v60, 0xffff0000, v60
	v_lshlrev_b32_e32 v69, 16, v61
	v_and_b32_e32 v61, 0xffff0000, v61
	v_mul_f32_e32 v58, v58, v58
	v_mul_f32_e32 v59, v59, v59
	v_mul_f32_e32 v60, v60, v60
	v_mul_f32_e32 v61, v61, v61
	v_fmac_f32_e32 v58, v66, v66
	v_fmac_f32_e32 v59, v67, v67
	v_fmac_f32_e32 v60, v68, v68
	v_fmac_f32_e32 v61, v69, v69
	v_add_f32_e32 v58, v58, v59
	v_add_f32_e32 v59, v60, v61
	v_add_f32_e32 v58, v58, v59
	s_waitcnt vmcnt(1)
	v_lshlrev_b32_e32 v59, 16, v62
	v_and_b32_e32 v60, 0xffff0000, v62
	v_and_b32_e32 v62, 0xffff0000, v63
	v_lshlrev_b32_e32 v61, 16, v63
	v_lshlrev_b32_e32 v63, 16, v64
	v_and_b32_e32 v64, 0xffff0000, v64
	v_lshlrev_b32_e32 v66, 16, v65
	v_and_b32_e32 v65, 0xffff0000, v65
	v_fmac_f32_e32 v60, 0.5, v55
	v_fmac_f32_e32 v62, 0.5, v57
	v_fmac_f32_e32 v59, 0.5, v54
	v_fmac_f32_e32 v61, 0.5, v56
	v_fmac_f32_e32 v63, 0.5, v50
	v_fmac_f32_e32 v64, 0.5, v51
	v_fmac_f32_e32 v66, 0.5, v52
	v_fmac_f32_e32 v65, 0.5, v53
	v_cvt_pk_bf16_f32 v52, v59, v60
	v_cvt_pk_bf16_f32 v53, v61, v62
	v_cvt_pk_bf16_f32 v54, v63, v64
	v_cvt_pk_bf16_f32 v55, v66, v65
	global_store_dwordx4 v[72:73], v[52:55], off offset:256
	v_and_b32_e32 v51, 0xffff0000, v52
	v_and_b32_e32 v57, 0xffff0000, v53
	v_and_b32_e32 v60, 0xffff0000, v54
	v_and_b32_e32 v62, 0xffff0000, v55
	v_lshlrev_b32_e32 v50, 16, v52
	v_lshlrev_b32_e32 v56, 16, v53
	v_lshlrev_b32_e32 v59, 16, v54
	v_lshlrev_b32_e32 v61, 16, v55
	v_mul_f32_e32 v51, v51, v51
	v_mul_f32_e32 v57, v57, v57
	v_mul_f32_e32 v60, v60, v60
	v_mul_f32_e32 v62, v62, v62
	v_fmac_f32_e32 v51, v50, v50
	v_fmac_f32_e32 v57, v56, v56
	v_fmac_f32_e32 v60, v59, v59
	v_fmac_f32_e32 v62, v61, v61
	v_add_f32_e32 v50, v51, v57
	v_add_f32_e32 v51, v60, v62
	v_add_f32_e32 v50, v50, v51
	v_add_f32_e32 v50, v58, v50
	v_mov_b32_e32 v206, v50
	v_mov_b32_e32 v207, v50
	s_nop 1
	v_permlane16_swap_b32_e32 v206, v207
	s_waitcnt lgkmcnt(0)
	v_add_f32_e32 v50, v206, v207
	v_mov_b32_e32 v206, v50
	v_mov_b32_e32 v207, v50
	s_nop 1
	v_permlane32_swap_b32_e32 v206, v207
	s_and_saveexec_b64 s[0:1], s[40:41]
	s_cbranch_execz .LBB0_366
	s_waitcnt lgkmcnt(0)
	v_add_f32_e32 v50, v206, v207
	v_fma_f32 v50, v50, s6, 0.5
	v_trunc_f32_e32 v50, v50
	v_mul_f32_e32 v51, 0x2f800000, v50
	v_floor_f32_e32 v51, v51
	v_fmac_f32_e32 v50, 0xcf800000, v51
	v_cvt_u32_f32_e32 v50, v50
	v_cvt_u32_f32_e32 v51, v51
	v_mov_b32_e32 v176, v50
	v_mov_b32_e32 v177, v51
.LBB0_366:
	s_or_b64 exec, exec, s[0:1]
	v_add_co_u32_e32 v56, vcc, 0x90000, v140
	s_mov_b64 s[0:1], 0x90000
	s_nop 0
	v_addc_co_u32_e32 v57, vcc, 0, v141, vcc
	global_load_dwordx4 v[52:55], v[56:57], off
	s_waitcnt lgkmcnt(0)
	v_lshl_add_u64 v[50:51], v[140:141], 0, s[0:1]
	s_waitcnt vmcnt(0)
	v_lshlrev_b32_e32 v58, 16, v52
	v_fmac_f32_e32 v58, 0.5, v46
	v_and_b32_e32 v46, 0xffff0000, v52
	v_fmac_f32_e32 v46, 0.5, v47
	v_lshlrev_b32_e32 v47, 16, v53
	v_fmac_f32_e32 v47, 0.5, v48
	v_and_b32_e32 v48, 0xffff0000, v53
	v_fmac_f32_e32 v48, 0.5, v49
	v_cvt_pk_bf16_f32 v46, v58, v46
	v_cvt_pk_bf16_f32 v47, v47, v48
	v_lshlrev_b32_e32 v48, 16, v54
	v_fmac_f32_e32 v48, 0.5, v42
	v_and_b32_e32 v42, 0xffff0000, v54
	v_fmac_f32_e32 v42, 0.5, v43
	v_and_b32_e32 v43, 0xffff0000, v55
	v_cvt_pk_bf16_f32 v48, v48, v42
	v_lshlrev_b32_e32 v42, 16, v55
	v_fmac_f32_e32 v43, 0.5, v45
	v_fmac_f32_e32 v42, 0.5, v44
	v_cvt_pk_bf16_f32 v49, v42, v43
	v_and_b32_e32 v43, 0xffff0000, v46
	v_lshlrev_b32_e32 v42, 16, v46
	v_and_b32_e32 v45, 0xffff0000, v47
	v_mul_f32_e32 v43, v43, v43
	v_lshlrev_b32_e32 v44, 16, v47
	v_fmac_f32_e32 v43, v42, v42
	v_mul_f32_e32 v42, v45, v45
	global_store_dwordx4 v[56:57], v[46:49], off
	v_fmac_f32_e32 v42, v44, v44
	v_add_f32_e32 v42, v43, v42
	v_lshlrev_b32_e32 v46, 16, v48
	v_and_b32_e32 v47, 0xffff0000, v48
	v_lshlrev_b32_e32 v48, 16, v49
	v_and_b32_e32 v49, 0xffff0000, v49
	v_mul_f32_e32 v43, v47, v47
	v_mul_f32_e32 v44, v49, v49
	v_fmac_f32_e32 v43, v46, v46
	v_fmac_f32_e32 v44, v48, v48
	v_add_f32_e32 v43, v43, v44
	v_add_f32_e32 v46, v42, v43
	global_load_dwordx4 v[42:45], v[50:51], off offset:256
	s_waitcnt vmcnt(0)
	v_lshlrev_b32_e32 v47, 16, v42
	v_fmac_f32_e32 v47, 0.5, v38
	v_and_b32_e32 v38, 0xffff0000, v42
	v_fmac_f32_e32 v38, 0.5, v39
	v_lshlrev_b32_e32 v39, 16, v43
	v_fmac_f32_e32 v39, 0.5, v40
	v_and_b32_e32 v40, 0xffff0000, v43
	v_fmac_f32_e32 v40, 0.5, v41
	v_cvt_pk_bf16_f32 v38, v47, v38
	v_cvt_pk_bf16_f32 v39, v39, v40
	v_lshlrev_b32_e32 v40, 16, v44
	v_fmac_f32_e32 v40, 0.5, v34
	v_and_b32_e32 v34, 0xffff0000, v44
	v_fmac_f32_e32 v34, 0.5, v35
	v_and_b32_e32 v35, 0xffff0000, v45
	v_cvt_pk_bf16_f32 v40, v40, v34
	v_lshlrev_b32_e32 v34, 16, v45
	v_fmac_f32_e32 v35, 0.5, v37
	v_fmac_f32_e32 v34, 0.5, v36
	v_cvt_pk_bf16_f32 v41, v34, v35
	v_and_b32_e32 v35, 0xffff0000, v38
	v_lshlrev_b32_e32 v34, 16, v38
	v_and_b32_e32 v37, 0xffff0000, v39
	v_mul_f32_e32 v35, v35, v35
	v_lshlrev_b32_e32 v36, 16, v39
	v_fmac_f32_e32 v35, v34, v34
	v_mul_f32_e32 v34, v37, v37
	global_store_dwordx4 v[50:51], v[38:41], off offset:256
	v_fmac_f32_e32 v34, v36, v36
	v_add_f32_e32 v34, v35, v34
	v_lshlrev_b32_e32 v38, 16, v40
	v_and_b32_e32 v39, 0xffff0000, v40
	v_lshlrev_b32_e32 v40, 16, v41
	v_and_b32_e32 v41, 0xffff0000, v41
	v_mul_f32_e32 v35, v39, v39
	v_mul_f32_e32 v36, v41, v41
	v_fmac_f32_e32 v35, v38, v38
	v_fmac_f32_e32 v36, v40, v40
	v_add_f32_e32 v35, v35, v36
	v_add_f32_e32 v34, v34, v35
	v_add_f32_e32 v34, v46, v34
	v_mov_b32_e32 v206, v34
	v_mov_b32_e32 v207, v34
	s_nop 1
	v_permlane16_swap_b32_e32 v206, v207
	s_waitcnt lgkmcnt(0)
	v_add_f32_e32 v34, v206, v207
	v_mov_b32_e32 v206, v34
	v_mov_b32_e32 v207, v34
	s_nop 1
	v_permlane32_swap_b32_e32 v206, v207
	s_and_saveexec_b64 s[0:1], s[40:41]
	s_cbranch_execz .LBB0_368
	s_waitcnt lgkmcnt(0)
	v_add_f32_e32 v34, v206, v207
	v_fma_f32 v34, v34, s6, 0.5
	v_trunc_f32_e32 v34, v34
	v_mul_f32_e32 v35, 0x2f800000, v34
	v_floor_f32_e32 v35, v35
	v_fmac_f32_e32 v34, 0xcf800000, v35
	v_cvt_u32_f32_e32 v34, v34
	v_cvt_u32_f32_e32 v35, v35
	v_mov_b32_e32 v178, v34
	v_mov_b32_e32 v179, v35
.LBB0_368:
	s_or_b64 exec, exec, s[0:1]
	v_add_co_u32_e32 v40, vcc, 0xa0000, v140
	s_mov_b64 s[0:1], 0xa0000
	s_nop 0
	v_addc_co_u32_e32 v41, vcc, 0, v141, vcc
	global_load_dwordx4 v[36:39], v[40:41], off
	s_waitcnt lgkmcnt(0)
	v_lshl_add_u64 v[34:35], v[140:141], 0, s[0:1]
	s_waitcnt vmcnt(0)
	v_lshlrev_b32_e32 v42, 16, v36
	v_fmac_f32_e32 v42, 0.5, v30
	v_and_b32_e32 v30, 0xffff0000, v36
	v_fmac_f32_e32 v30, 0.5, v31
	v_lshlrev_b32_e32 v31, 16, v37
	v_fmac_f32_e32 v31, 0.5, v32
	v_and_b32_e32 v32, 0xffff0000, v37
	v_fmac_f32_e32 v32, 0.5, v33
	v_cvt_pk_bf16_f32 v30, v42, v30
	v_cvt_pk_bf16_f32 v31, v31, v32
	v_lshlrev_b32_e32 v32, 16, v38
	v_fmac_f32_e32 v32, 0.5, v26
	v_and_b32_e32 v26, 0xffff0000, v38
	v_fmac_f32_e32 v26, 0.5, v27
	v_and_b32_e32 v27, 0xffff0000, v39
	v_cvt_pk_bf16_f32 v32, v32, v26
	v_lshlrev_b32_e32 v26, 16, v39
	v_fmac_f32_e32 v27, 0.5, v29
	v_fmac_f32_e32 v26, 0.5, v28
	v_cvt_pk_bf16_f32 v33, v26, v27
	v_and_b32_e32 v27, 0xffff0000, v30
	v_lshlrev_b32_e32 v26, 16, v30
	v_and_b32_e32 v29, 0xffff0000, v31
	v_mul_f32_e32 v27, v27, v27
	v_lshlrev_b32_e32 v28, 16, v31
	v_fmac_f32_e32 v27, v26, v26
	v_mul_f32_e32 v26, v29, v29
	global_store_dwordx4 v[40:41], v[30:33], off
	v_fmac_f32_e32 v26, v28, v28
	v_add_f32_e32 v26, v27, v26
	v_lshlrev_b32_e32 v30, 16, v32
	v_and_b32_e32 v31, 0xffff0000, v32
	v_lshlrev_b32_e32 v32, 16, v33
	v_and_b32_e32 v33, 0xffff0000, v33
	v_mul_f32_e32 v27, v31, v31
	v_mul_f32_e32 v28, v33, v33
	v_fmac_f32_e32 v27, v30, v30
	v_fmac_f32_e32 v28, v32, v32
	v_add_f32_e32 v27, v27, v28
	v_add_f32_e32 v30, v26, v27
	global_load_dwordx4 v[26:29], v[34:35], off offset:256
	s_waitcnt vmcnt(0)
	v_lshlrev_b32_e32 v31, 16, v26
	v_fmac_f32_e32 v31, 0.5, v22
	v_and_b32_e32 v22, 0xffff0000, v26
	v_fmac_f32_e32 v22, 0.5, v23
	v_lshlrev_b32_e32 v23, 16, v27
	v_fmac_f32_e32 v23, 0.5, v24
	v_and_b32_e32 v24, 0xffff0000, v27
	v_fmac_f32_e32 v24, 0.5, v25
	v_cvt_pk_bf16_f32 v22, v31, v22
	v_cvt_pk_bf16_f32 v23, v23, v24
	v_lshlrev_b32_e32 v24, 16, v28
	v_fmac_f32_e32 v24, 0.5, v18
	v_and_b32_e32 v18, 0xffff0000, v28
	v_fmac_f32_e32 v18, 0.5, v19
	v_and_b32_e32 v19, 0xffff0000, v29
	v_cvt_pk_bf16_f32 v24, v24, v18
	v_lshlrev_b32_e32 v18, 16, v29
	v_fmac_f32_e32 v19, 0.5, v21
	v_fmac_f32_e32 v18, 0.5, v20
	v_cvt_pk_bf16_f32 v25, v18, v19
	v_and_b32_e32 v19, 0xffff0000, v22
	v_lshlrev_b32_e32 v18, 16, v22
	v_and_b32_e32 v21, 0xffff0000, v23
	v_mul_f32_e32 v19, v19, v19
	v_lshlrev_b32_e32 v20, 16, v23
	v_fmac_f32_e32 v19, v18, v18
	v_mul_f32_e32 v18, v21, v21
	global_store_dwordx4 v[34:35], v[22:25], off offset:256
	v_fmac_f32_e32 v18, v20, v20
	v_add_f32_e32 v18, v19, v18
	v_lshlrev_b32_e32 v22, 16, v24
	v_and_b32_e32 v23, 0xffff0000, v24
	v_lshlrev_b32_e32 v24, 16, v25
	v_and_b32_e32 v25, 0xffff0000, v25
	v_mul_f32_e32 v19, v23, v23
	v_mul_f32_e32 v20, v25, v25
	v_fmac_f32_e32 v19, v22, v22
	v_fmac_f32_e32 v20, v24, v24
	v_add_f32_e32 v19, v19, v20
	v_add_f32_e32 v18, v18, v19
	v_add_f32_e32 v18, v30, v18
	v_mov_b32_e32 v206, v18
	v_mov_b32_e32 v207, v18
	s_nop 1
	v_permlane16_swap_b32_e32 v206, v207
	s_waitcnt lgkmcnt(0)
	v_add_f32_e32 v18, v206, v207
	v_mov_b32_e32 v206, v18
	v_mov_b32_e32 v207, v18
	s_nop 1
	v_permlane32_swap_b32_e32 v206, v207
	s_and_saveexec_b64 s[0:1], s[40:41]
	s_cbranch_execz .LBB0_370
	s_waitcnt lgkmcnt(0)
	v_add_f32_e32 v18, v206, v207
	v_fma_f32 v18, v18, s6, 0.5
	v_trunc_f32_e32 v18, v18
	v_mul_f32_e32 v19, 0x2f800000, v18
	v_floor_f32_e32 v19, v19
	v_fmac_f32_e32 v18, 0xcf800000, v19
	v_cvt_u32_f32_e32 v18, v18
	v_cvt_u32_f32_e32 v19, v19
	v_mov_b32_e32 v180, v18
	v_mov_b32_e32 v181, v19
.LBB0_370:
	s_or_b64 exec, exec, s[0:1]
	v_add_co_u32_e32 v22, vcc, 0xb0000, v140
	s_mov_b64 s[0:1], 0xb0000
	s_nop 0
	v_addc_co_u32_e32 v23, vcc, 0, v141, vcc
	s_waitcnt lgkmcnt(0)
	global_load_dwordx4 v[18:21], v[22:23], off
	v_lshl_add_u64 v[24:25], v[140:141], 0, s[0:1]
	s_waitcnt vmcnt(0)
	v_lshlrev_b32_e32 v26, 16, v18
	v_and_b32_e32 v18, 0xffff0000, v18
	v_lshlrev_b32_e32 v27, 16, v19
	v_and_b32_e32 v19, 0xffff0000, v19
	v_lshlrev_b32_e32 v28, 16, v20
	v_and_b32_e32 v20, 0xffff0000, v20
	v_lshlrev_b32_e32 v29, 16, v21
	v_and_b32_e32 v21, 0xffff0000, v21
	v_fmac_f32_e32 v26, 0.5, v14
	v_fmac_f32_e32 v18, 0.5, v15
	v_fmac_f32_e32 v27, 0.5, v16
	v_fmac_f32_e32 v19, 0.5, v17
	v_fmac_f32_e32 v28, 0.5, v10
	v_fmac_f32_e32 v20, 0.5, v11
	v_fmac_f32_e32 v29, 0.5, v12
	v_fmac_f32_e32 v21, 0.5, v13
	v_cvt_pk_bf16_f32 v10, v26, v18
	v_cvt_pk_bf16_f32 v11, v27, v19
	v_cvt_pk_bf16_f32 v12, v28, v20
	v_cvt_pk_bf16_f32 v13, v29, v21
	global_load_dwordx4 v[14:17], v[24:25], off offset:256
	v_lshlrev_b32_e32 v18, 16, v10
	global_store_dwordx4 v[22:23], v[10:13], off
	v_lshlrev_b32_e32 v19, 16, v11
	v_lshlrev_b32_e32 v20, 16, v12
	v_and_b32_e32 v10, 0xffff0000, v10
	v_and_b32_e32 v11, 0xffff0000, v11
	v_and_b32_e32 v12, 0xffff0000, v12
	v_lshlrev_b32_e32 v21, 16, v13
	v_and_b32_e32 v13, 0xffff0000, v13
	v_mul_f32_e32 v10, v10, v10
	v_mul_f32_e32 v11, v11, v11
	v_mul_f32_e32 v12, v12, v12
	v_mul_f32_e32 v13, v13, v13
	v_fmac_f32_e32 v10, v18, v18
	v_fmac_f32_e32 v11, v19, v19
	v_fmac_f32_e32 v12, v20, v20
	v_fmac_f32_e32 v13, v21, v21
	v_add_f32_e32 v10, v10, v11
	v_add_f32_e32 v11, v12, v13
	v_add_f32_e32 v10, v10, v11
	s_waitcnt vmcnt(1)
	v_lshlrev_b32_e32 v11, 16, v14
	v_and_b32_e32 v12, 0xffff0000, v14
	v_and_b32_e32 v14, 0xffff0000, v15
	v_lshlrev_b32_e32 v13, 16, v15
	v_lshlrev_b32_e32 v15, 16, v16
	v_and_b32_e32 v16, 0xffff0000, v16
	v_lshlrev_b32_e32 v18, 16, v17
	v_and_b32_e32 v17, 0xffff0000, v17
	v_fmac_f32_e32 v12, 0.5, v7
	v_fmac_f32_e32 v14, 0.5, v9
	v_fmac_f32_e32 v11, 0.5, v6
	v_fmac_f32_e32 v13, 0.5, v8
	v_fmac_f32_e32 v15, 0.5, v2
	v_fmac_f32_e32 v16, 0.5, v3
	v_fmac_f32_e32 v18, 0.5, v4
	v_fmac_f32_e32 v17, 0.5, v5
	v_cvt_pk_bf16_f32 v4, v11, v12
	v_cvt_pk_bf16_f32 v5, v13, v14
	v_cvt_pk_bf16_f32 v6, v15, v16
	v_cvt_pk_bf16_f32 v7, v18, v17
	global_store_dwordx4 v[24:25], v[4:7], off offset:256
	v_and_b32_e32 v3, 0xffff0000, v4
	v_and_b32_e32 v9, 0xffff0000, v5
	v_and_b32_e32 v12, 0xffff0000, v6
	v_and_b32_e32 v14, 0xffff0000, v7
	v_lshlrev_b32_e32 v2, 16, v4
	v_lshlrev_b32_e32 v8, 16, v5
	v_lshlrev_b32_e32 v11, 16, v6
	v_lshlrev_b32_e32 v13, 16, v7
	v_mul_f32_e32 v3, v3, v3
	v_mul_f32_e32 v9, v9, v9
	v_mul_f32_e32 v12, v12, v12
	v_mul_f32_e32 v14, v14, v14
	v_fmac_f32_e32 v3, v2, v2
	v_fmac_f32_e32 v9, v8, v8
	v_fmac_f32_e32 v12, v11, v11
	v_fmac_f32_e32 v14, v13, v13
	v_add_f32_e32 v2, v3, v9
	v_add_f32_e32 v3, v12, v14
	v_add_f32_e32 v2, v2, v3
	v_add_f32_e32 v2, v10, v2
	v_mov_b32_e32 v206, v2
	v_mov_b32_e32 v207, v2
	s_nop 1
	v_permlane16_swap_b32_e32 v206, v207
	s_waitcnt lgkmcnt(0)
	v_add_f32_e32 v2, v206, v207
	v_mov_b32_e32 v206, v2
	v_mov_b32_e32 v207, v2
	s_nop 1
	v_permlane32_swap_b32_e32 v206, v207
	s_and_saveexec_b64 s[0:1], s[40:41]
	s_cbranch_execz .LBB0_372
	s_waitcnt lgkmcnt(0)
	v_add_f32_e32 v2, v206, v207
	v_fma_f32 v2, v2, s6, 0.5
	v_trunc_f32_e32 v2, v2
	v_mul_f32_e32 v3, 0x2f800000, v2
	v_floor_f32_e32 v3, v3
	v_fmac_f32_e32 v2, 0xcf800000, v3
	v_cvt_u32_f32_e32 v2, v2
	v_cvt_u32_f32_e32 v3, v3
	global_atomic_add_x2 v[114:115], v[2:3], off offset:1408
